# adds nt on P3 read-once loads (attention q/z_b, scan U slices)
# speedup vs baseline: 1.0442x; 1.0022x over previous
; __device__ __forceinline__ float bflo(unsigned w) { return __uint_as_float(w << 16); }
; __device__ __forceinline__ float bfhi(unsigned w) { return __uint_as_float(w & 0xffff0000u); }
; __device__ __forceinline__ void scan_chain(const Params& P, bool smp, int s, int h, int sl, int lane) {
;     const int l15 = lane & 15, q4 = lane >> 4, e = 16 * sl + l15;
;     const int cu0 = smp ? 1024 + s : s * 128, nsteps = smp ? 1 : 128;
;     f32x4 S[4];
; #pragma unroll
;     for (int tau = 0; tau < 4; ++tau)
; #pragma unroll
;         for (int r = 0; r < 4; ++r) S[tau][r] = smp ? P.state_gdn[(((size_t)s * 8 + h) * 64 + 16 * tau + 4 * q4 + r) * 64 + e] : 0.f;
;     const float* GT = (const float*)(P.ws + WS_GT);
;     float* OA = (float*)((unsigned char*)P.out + YO_OA); float* OAS = (float*)(P.ws + WS_OAS);
; #pragma unroll 1
;     for (int n = 0; n < nsteps; ++n) {
;         const int cu = cu0 + n; const unsigned char* ops = P.ws + WS_OPS + ((size_t)cu * 8 + h) * OPS_UNIT;
;         const float gt = GT[cu * 8 + h];
;         const bf16x8* Wf = (const bf16x8*)(ops + OPS_W) + lane; const bf16x8* KT = (const bf16x8*)(ops + OPS_KT) + lane;
;         const bf16x8* QD = (const bf16x8*)(ops + OPS_QD) + lane; const bf16x8* QK = (const bf16x8*)(ops + OPS_QK) + lane;
;         const v2u* Up = (const v2u*)(ops + OPS_U) + (sl * 4) * 64 + lane;
;         bf16x8 Sb[2]; Sb[0] = pack8(S[0], S[1]); Sb[1] = pack8(S[2], S[3]);
;         f32x4 vn[4];
; #pragma unroll
;         for (int tau = 0; tau < 4; ++tau) { f32x4 av = {0.f, 0.f, 0.f, 0.f}; av = mfma16(Wf[(2 * tau) * 64], Sb[0], av); av = mfma16(Wf[(2 * tau + 1) * 64], Sb[1], av);
;             const v2u ub = Up[tau * 64]; const f32x4 u = {bflo(ub.x), bfhi(ub.x), bflo(ub.y), bfhi(ub.y)}; vn[tau] = u - av; }
;         bf16x8 Vb[2]; Vb[0] = pack8(vn[0], vn[1]); Vb[1] = pack8(vn[2], vn[3]);
;         f32x4 ao[4];
; #pragma unroll
;         for (int tau = 0; tau < 4; ++tau) { f32x4 a = {0.f, 0.f, 0.f, 0.f}; a = mfma16(QD[(2 * tau) * 64], Sb[0], a); a = mfma16(QD[(2 * tau + 1) * 64], Sb[1], a);
;             a = mfma16(QK[((tau < 2) ? tau : 2 * tau - 2) * 64], Vb[0], a); if (tau >= 2) a = mfma16(QK[(2 * tau - 1) * 64], Vb[1], a); ao[tau] = a; }
; #pragma unroll
;         for (int tau = 0; tau < 4; ++tau) { f32x4 a = S[tau] * gt; a = mfma16(KT[(2 * tau) * 64], Vb[0], a); a = mfma16(KT[(2 * tau + 1) * 64], Vb[1], a); S[tau] = a; }
.LBB0_639:
	v_readlane_b32 s18, v247, 0
	v_readlane_b32 s19, v247, 1
	s_add_u32 s29, s18, 0x1400000
	s_addc_u32 s30, s19, 0
	s_ashr_i32 s8, s96, 3
	s_lshl_b32 s0, s8, 7
	s_ashr_i32 s1, s0, 31
	s_and_b32 s2, s96, 7
	s_lshl_b64 s[14:15], s[0:1], 3
	s_add_u32 s10, s18, 0x3600000
	s_addc_u32 s11, s19, 0
	s_add_u32 s4, s18, 0xb700000
	s_addc_u32 s5, s19, 0
	s_ashr_i32 s9, s8, 31
	s_add_u32 s22, s18, 0x23900000
	s_addc_u32 s23, s19, 0
	s_or_b32 s12, s14, s2
	s_mul_i32 s13, s15, 0xa000
	s_mul_hi_u32 s16, s12, 0xa000
	s_add_i32 s16, s16, s13
	s_mul_i32 s12, s12, 0xa000
	s_add_u32 s12, s22, s12
	s_addc_u32 s13, s23, s16
	s_add_u32 s16, s18, 0x3d300000
	s_addc_u32 s17, s19, 0
	s_lshl_b32 s28, s96, 1
	s_ashr_i32 s18, s40, 8
	s_add_i32 s18, s18, s28
	s_ashr_i32 s26, s18, 3
	s_ashr_i32 s27, s26, 31
	s_and_b32 s34, s18, 7
	v_lshrrev_b32_e32 v1, 4, v164
	s_lshl_b64 s[18:19], s[26:27], 9
	v_and_b32_e32 v30, 15, v35
	v_lshl_or_b32 v2, v1, 2, s18
	s_bfe_u32 s24, s40, 0x20006
	v_lshl_or_b32 v2, s34, 6, v2
	v_mov_b32_e32 v3, s19
	v_lshlrev_b32_e32 v4, 2, v30
	v_mov_b32_e32 v165, 0
	v_lshl_or_b32 v4, s24, 6, v4
	v_mov_b32_e32 v5, v165
	v_lshlrev_b64 v[2:3], 8, v[2:3]
	v_lshl_add_u64 v[14:15], s[74:75], 0, v[4:5]
	v_or_b32_e32 v10, 0x1100, v2
	v_mov_b32_e32 v11, v3
	v_or_b32_e32 v8, 0x1000, v2
	v_mov_b32_e32 v9, v3
	v_lshl_add_u64 v[16:17], v[14:15], 0, v[10:11]
	v_or_b32_e32 v10, 0x1200, v2
	v_lshl_add_u64 v[6:7], v[14:15], 0, v[2:3]
	v_lshl_add_u64 v[8:9], v[14:15], 0, v[8:9]
	v_lshl_add_u64 v[18:19], v[14:15], 0, v[10:11]
	v_or_b32_e32 v10, 0x1300, v2
	s_add_i32 s18, s26, 0x400
	v_lshl_add_u64 v[20:21], v[14:15], 0, v[10:11]
	global_load_dword v10, v[6:7], off
	global_load_dword v11, v[6:7], off offset:256
	global_load_dword v12, v[6:7], off offset:512
	global_load_dword v13, v[6:7], off offset:768
	s_nop 0
	global_load_dword v6, v[8:9], off
	global_load_dword v7, v[16:17], off
	s_nop 0
	global_load_dword v8, v[18:19], off
	global_load_dword v9, v[20:21], off
	v_or_b32_e32 v18, 0x2100, v2
	v_mov_b32_e32 v19, v3
	s_ashr_i32 s19, s18, 31
	v_lshl_add_u64 v[22:23], v[14:15], 0, v[18:19]
	v_or_b32_e32 v18, 0x2200, v2
	s_lshl_b64 s[20:21], s[18:19], 3
	v_lshl_add_u64 v[28:29], v[14:15], 0, v[18:19]
	v_or_b32_e32 v18, 0x2300, v2
	s_or_b32 s19, s20, s34
	v_lshl_add_u64 v[32:33], v[14:15], 0, v[18:19]
	v_or_b32_e32 v18, 0x3000, v2
	s_mul_i32 s20, s21, 0xa000
	s_mul_hi_u32 s21, s19, 0xa000
	v_lshl_add_u64 v[36:37], v[14:15], 0, v[18:19]
	v_or_b32_e32 v18, 0x3100, v2
	s_add_i32 s21, s21, s20
	s_mul_i32 s19, s19, 0xa000
	v_or_b32_e32 v16, 0x2000, v2
	v_mov_b32_e32 v17, v3
	v_lshl_add_u64 v[38:39], v[14:15], 0, v[18:19]
	v_or_b32_e32 v18, 0x3200, v2
	s_add_u32 s20, s22, s19
	v_lshl_add_u64 v[16:17], v[14:15], 0, v[16:17]
	v_lshl_add_u64 v[40:41], v[14:15], 0, v[18:19]
	v_or_b32_e32 v2, 0x3300, v2
	s_addc_u32 s21, s23, s21
	v_lshlrev_b32_e32 v18, 4, v164
	v_lshl_add_u64 v[2:3], v[14:15], 0, v[2:3]
	global_load_dwordx4 v[24:27], v18, s[20:21]
	global_load_dword v20, v[16:17], off
	global_load_dword v21, v[22:23], off
	s_nop 0
	global_load_dword v22, v[28:29], off
	global_load_dword v23, v[32:33], off
	global_load_dword v14, v[36:37], off
	global_load_dword v15, v[38:39], off
	global_load_dword v16, v[40:41], off
	global_load_dword v17, v[2:3], off
	s_lshl_b32 s18, s18, 3
	global_load_dwordx4 v[36:39], v18, s[20:21] offset:1024
	global_load_dwordx4 v[40:43], v18, s[20:21] offset:2048
	s_or_b32 s18, s18, s34
	s_ashr_i32 s19, s18, 31
	s_lshl_b64 s[18:19], s[18:19], 2
	s_add_u32 s18, s29, s18
	s_addc_u32 s19, s30, s19
	s_lshl_b32 s22, s24, 11
	s_add_u32 s22, s20, s22
	s_addc_u32 s23, s21, 0
	v_lshlrev_b32_e32 v2, 3, v164
	v_mov_b32_e32 v3, v165
	v_lshl_add_u64 v[32:33], s[22:23], 0, v[2:3]
	s_mov_b32 s31, 0x8000
	v_mov_b32_e32 v19, v165
	v_add_co_u32_e32 v44, vcc, s31, v32
	s_movk_i32 s36, 0x2000
	v_lshl_add_u64 v[28:29], s[20:21], 0, v[18:19]
	v_addc_co_u32_e32 v45, vcc, 0, v33, vcc
	v_add_co_u32_e32 v82, vcc, s36, v28
	global_load_dwordx2 v[96:97], v[44:45], off
	s_nop 0
	global_load_dwordx4 v[44:47], v18, s[20:21] offset:3072
	v_addc_co_u32_e32 v83, vcc, 0, v29, vcc
	global_load_dwordx4 v[48:51], v[82:83], off offset:-4096
	s_movk_i32 s35, 0x1000
	v_add_co_u32_e32 v60, vcc, s35, v28
	s_mov_b64 s[24:25], 0x8000
	s_nop 0
	v_addc_co_u32_e32 v61, vcc, 0, v29, vcc
	global_load_dwordx4 v[52:55], v[60:61], off offset:1024
	v_lshl_add_u64 v[32:33], v[32:33], 0, s[24:25]
	global_load_dwordx2 v[98:99], v[32:33], off offset:512
	global_load_dwordx4 v[56:59], v[60:61], off offset:2048
	s_nop 0
	global_load_dwordx4 v[60:63], v[60:61], off offset:3072
	s_movk_i32 s22, 0x4000
	s_mov_b64 s[20:21], 0x4000
	v_add_co_u32_e32 v64, vcc, s22, v28
	v_lshl_add_u64 v[68:69], v[28:29], 0, s[20:21]
	s_nop 0
	v_addc_co_u32_e32 v65, vcc, 0, v29, vcc
	s_movk_i32 s20, 0x6000
	v_add_co_u32_e32 v72, vcc, s20, v28
	global_load_dwordx4 v[64:67], v[64:65], off
	s_nop 0
	v_addc_co_u32_e32 v73, vcc, 0, v29, vcc
	global_load_dwordx4 v[68:71], v[68:69], off offset:1024
	s_nop 0
	global_load_dwordx4 v[72:75], v[72:73], off
	s_nop 0
	global_load_dwordx2 v[100:101], v[32:33], off offset:1024
	s_nop 0
	global_load_dwordx2 v[32:33], v[32:33], off offset:1536
	s_nop 0
	global_load_dword v34, v165, s[18:19]
	s_waitcnt vmcnt(30)
	v_cvt_pk_bf16_f32 v76, v10, v11
	s_waitcnt vmcnt(28)
	v_cvt_pk_bf16_f32 v77, v12, v13
	s_waitcnt vmcnt(26)
	v_cvt_pk_bf16_f32 v78, v6, v7
	s_waitcnt vmcnt(24)
	v_cvt_pk_bf16_f32 v79, v8, v9
	s_mov_b64 s[18:19], 0x2000
	v_lshl_add_u64 v[92:93], v[28:29], 0, s[18:19]
	s_waitcnt vmcnt(23)
	v_mfma_f32_16x16x32_bf16 v[24:27], v[24:27], v[76:79], 0
	global_load_dwordx4 v[84:87], v[82:83], off
	global_load_dwordx4 v[88:91], v[92:93], off offset:1024
	s_waitcnt vmcnt(23)
; __device__ __forceinline__ float bflo(unsigned w) { return __uint_as_float(w << 16); }
; __device__ __forceinline__ void scan_chain(const Params& P, bool smp, int s, int h, int sl, int lane) {
;     ...
;         for (int tau = 0; tau < 4; ++tau) { f32x4 av = {0.f, 0.f, 0.f, 0.f}; av = mfma16(Wf[(2 * tau) * 64], Sb[0], av); av = mfma16(Wf[(2 * tau + 1) * 64], Sb[1], av);
;             const v2u ub = Up[tau * 64]; const f32x4 u = {bflo(ub.x), bfhi(ub.x), bflo(ub.y), bfhi(ub.y)}; vn[tau] = u - av; }
;         bf16x8 Vb[2]; Vb[0] = pack8(vn[0], vn[1]); Vb[1] = pack8(vn[2], vn[3]);
;         f32x4 ao[4];
; #pragma unroll
;         for (int tau = 0; tau < 4; ++tau) { f32x4 a = {0.f, 0.f, 0.f, 0.f}; a = mfma16(QD[(2 * tau) * 64], Sb[0], a); a = mfma16(QD[(2 * tau + 1) * 64], Sb[1], a);
;             a = mfma16(QK[((tau < 2) ? tau : 2 * tau - 2) * 64], Vb[0], a); if (tau >= 2) a = mfma16(QK[(2 * tau - 1) * 64], Vb[1], a); ao[tau] = a; }
; #pragma unroll
;         for (int tau = 0; tau < 4; ++tau) { f32x4 a = S[tau] * gt; a = mfma16(KT[(2 * tau) * 64], Vb[0], a); a = mfma16(KT[(2 * tau + 1) * 64], Vb[1], a); S[tau] = a; }
;         if (!smp) { float* op = OA + ((size_t)s * TP + n * 64) * 512 + h * 64 + e;
; #pragma unroll
;             for (int tau = 0; tau < 4; ++tau)
; #pragma unroll
;                 for (int r = 0; r < 4; ++r) op[(size_t)(16 * tau + 4 * q4 + r) * 512] = ao[tau][r];
;         } else { float* op = OAS + ((size_t)s * 16) * 512 + h * 64 + e;
; #pragma unroll
;             for (int r = 0; r < 4; ++r) op[(size_t)(4 * q4 + r) * 512] = ao[0][r]; }
;     }
;     float* so = P.out + (smp ? O_GS : O_GP) + (((size_t)s * 8 + h) * 64) * 64 + e;
; #pragma unroll
;     for (int tau = 0; tau < 4; ++tau)
; #pragma unroll
;         for (int r = 0; r < 4; ++r) so[(size_t)(16 * tau + 4 * q4 + r) * 64] = S[tau][r];
; __global__ void __launch_bounds__(NWAVES * 64, 2) fwd_kernel(Params P) {
;     ...
;             asm volatile("s_waitcnt vmcnt(0)" ::: "memory"); __syncthreads();
;             {
;                 const int pr = (int)blockIdx.x * 2 + (tid >> 8), sp = pr >> 3, hp_ = pr & 7, t = (tid >> 4) & 15, part = tid & 15;
;                 const size_t row = (size_t)sp * 16 + t;
;                 const f32x4 o4 = *(const f32x4*)((const float*)(ws + WS_OAS) + row * 512 + hp_ * 64 + 4 * part);
	v_cvt_pk_bf16_f32 v80, v20, v21
	s_waitcnt vmcnt(21)
	v_cvt_pk_bf16_f32 v81, v22, v23
	s_waitcnt vmcnt(15)
	v_mfma_f32_16x16x32_bf16 v[40:43], v[40:43], v[76:79], 0
	v_cvt_pk_bf16_f32 v82, v14, v15
	v_cvt_pk_bf16_f32 v83, v16, v17
	s_movk_i32 s18, 0x3000
	v_readlane_b32 s72, v247, 7
	v_mfma_f32_16x16x32_bf16 v[24:27], v[36:39], v[80:83], v[24:27]
	global_load_dwordx4 v[36:39], v[92:93], off offset:2048
	v_readlane_b32 s82, v247, 17
	global_load_dwordx4 v[92:95], v[92:93], off offset:3072
	s_waitcnt vmcnt(15)
	v_mfma_f32_16x16x32_bf16 v[40:43], v[44:47], v[80:83], v[40:43]
	v_lshlrev_b32_e32 v19, 16, v96
	v_and_b32_e32 v31, 0xffff0000, v96
	s_nop 0
	v_sub_f32_e32 v31, v31, v25
	s_waitcnt vmcnt(14)
	v_mfma_f32_16x16x32_bf16 v[44:47], v[48:51], v[76:79], 0
	v_lshlrev_b32_e32 v48, 16, v97
	v_and_b32_e32 v49, 0xffff0000, v97
	v_sub_f32_e32 v96, v49, v27
	s_waitcnt vmcnt(13)
	v_mfma_f32_16x16x32_bf16 v[44:47], v[52:55], v[80:83], v[44:47]
	v_sub_f32_e32 v52, v48, v26
	v_sub_f32_e32 v19, v19, v24
	s_waitcnt vmcnt(12)
	v_lshlrev_b32_e32 v53, 16, v98
	s_waitcnt vmcnt(11)
	v_mfma_f32_16x16x32_bf16 v[24:27], v[56:59], v[76:79], 0
	v_and_b32_e32 v54, 0xffff0000, v98
	v_lshlrev_b32_e32 v48, 16, v99
	v_sub_f32_e32 v53, v53, v40
	s_waitcnt vmcnt(10)
	v_mfma_f32_16x16x32_bf16 v[24:27], v[60:63], v[80:83], v[24:27]
	v_cvt_pk_bf16_f32 v40, v19, v31
	v_sub_f32_e32 v55, v48, v42
	s_waitcnt vmcnt(6)
	v_lshlrev_b32_e32 v19, 16, v100
	v_and_b32_e32 v31, 0xffff0000, v100
	v_sub_f32_e32 v42, v54, v41
	v_sub_f32_e32 v31, v31, v45
	v_sub_f32_e32 v19, v19, v44
	v_cvt_pk_bf16_f32 v41, v52, v96
	v_cvt_pk_bf16_f32 v42, v53, v42
	v_lshlrev_b32_e32 v52, 16, v101
	v_and_b32_e32 v53, 0xffff0000, v101
	v_cvt_pk_bf16_f32 v44, v19, v31
	s_waitcnt vmcnt(5)
	v_lshlrev_b32_e32 v19, 16, v32
	v_and_b32_e32 v31, 0xffff0000, v32
	v_lshlrev_b32_e32 v32, 16, v33
	v_sub_f32_e32 v47, v53, v47
	v_sub_f32_e32 v46, v52, v46
	v_and_b32_e32 v33, 0xffff0000, v33
	v_sub_f32_e32 v52, v32, v26
	v_add_co_u32_e32 v32, vcc, s18, v28
	v_cvt_pk_bf16_f32 v45, v46, v47
	v_sub_f32_e32 v47, v33, v27
	v_addc_co_u32_e32 v33, vcc, 0, v29, vcc
	global_load_dwordx4 v[26:29], v[32:33], off offset:3072
	global_load_dwordx4 v[56:59], v[32:33], off offset:2048
	v_and_b32_e32 v49, 0xffff0000, v99
	v_sub_f32_e32 v43, v49, v43
	v_cvt_pk_bf16_f32 v43, v55, v43
	v_cvt_pk_bf16_f32 v47, v52, v47
	global_load_dwordx4 v[52:55], v[32:33], off
	s_waitcnt vmcnt(7)
	v_pk_mul_f32 v[8:9], v[8:9], v[34:35] op_sel_hi:[1,0]
	v_pk_mul_f32 v[6:7], v[6:7], v[34:35] op_sel_hi:[1,0]
	v_mfma_f32_16x16x32_bf16 v[48:51], v[64:67], v[76:79], 0
	s_lshl_b64 s[18:19], s[26:27], 15
	s_add_u32 s18, s16, s18
	v_pk_mul_f32 v[16:17], v[16:17], v[34:35] op_sel_hi:[1,0]
	s_waitcnt vmcnt(4)
	v_mfma_f32_16x16x32_bf16 v[6:9], v[36:39], v[40:43], v[6:9]
	global_load_dwordx4 v[36:39], v[32:33], off offset:1024
	v_pk_mul_f32 v[14:15], v[14:15], v[34:35] op_sel_hi:[1,0]
	s_addc_u32 s19, s17, s19
	v_mfma_f32_16x16x32_bf16 v[48:51], v[68:71], v[80:83], v[48:51]
	s_lshl_b32 s20, s34, 8
	s_add_u32 s18, s18, s20
	v_sub_f32_e32 v25, v31, v25
	s_waitcnt vmcnt(2)
	v_mfma_f32_16x16x32_bf16 v[14:17], v[56:59], v[40:43], v[14:17]
	v_sub_f32_e32 v19, v19, v24
	s_addc_u32 s19, s19, 0
	v_cvt_pk_bf16_f32 v46, v19, v25
	v_mfma_f32_16x16x32_bf16 v[48:51], v[72:75], v[40:43], v[48:51]
	v_lshl_add_u64 v[24:25], s[18:19], 0, v[4:5]
	s_lshl_b64 s[18:19], s[26:27], 17
	v_pk_mul_f32 v[12:13], v[12:13], v[34:35] op_sel_hi:[1,0]
	v_pk_mul_f32 v[10:11], v[10:11], v[34:35] op_sel_hi:[1,0]
	v_mfma_f32_16x16x32_bf16 v[14:17], v[26:29], v[44:47], v[14:17]
	v_lshlrev_b32_e32 v26, 13, v1
	v_mov_b32_e32 v27, v165
	s_add_u32 s18, s54, s18
	v_mfma_f32_16x16x32_bf16 v[10:13], v[84:87], v[40:43], v[10:13]
	v_lshl_add_u64 v[24:25], v[24:25], 0, v[26:27]
	s_addc_u32 s19, s55, s19
	s_lshl_b32 s20, s34, 14
	global_store_dword v[24:25], v48, off
	global_store_dword v[24:25], v49, off offset:2048
	v_add_co_u32_e32 v24, vcc, s35, v24
	s_add_u32 s18, s18, s20
	s_nop 0
	v_addc_co_u32_e32 v25, vcc, 0, v25, vcc
	s_addc_u32 s19, s19, 0
	v_pk_mul_f32 v[22:23], v[22:23], v[34:35] op_sel_hi:[1,0]
	v_pk_mul_f32 v[20:21], v[20:21], v[34:35] op_sel_hi:[1,0]
	global_store_dword v[24:25], v50, off
	global_store_dword v[24:25], v51, off offset:2048
	v_lshl_add_u64 v[4:5], s[18:19], 0, v[4:5]
	v_lshlrev_b32_e32 v24, 10, v1
	v_mov_b32_e32 v25, v165
	v_mfma_f32_16x16x32_bf16 v[10:13], v[88:91], v[44:47], v[10:13]
	v_lshl_add_u64 v[4:5], v[4:5], 0, v[24:25]
	s_mov_b64 s[18:19], 0x1126c000
	v_lshl_add_u64 v[24:25], v[4:5], 0, s[18:19]
	s_waitcnt vmcnt(5)
	v_mfma_f32_16x16x32_bf16 v[20:23], v[52:55], v[40:43], v[20:23]
	s_mov_b32 s18, 0x1126d000
	v_add_co_u32_e32 v26, vcc, s18, v4
	v_mfma_f32_16x16x32_bf16 v[6:9], v[92:95], v[44:47], v[6:9]
	s_nop 0
	v_addc_co_u32_e32 v27, vcc, 0, v5, vcc
	s_mov_b32 s18, 0x1126e000
	s_waitcnt vmcnt(4)
	v_mfma_f32_16x16x32_bf16 v[20:23], v[36:39], v[44:47], v[20:23]
	global_store_dword v[26:27], v10, off offset:-4096
	global_store_dword v[24:25], v11, off offset:256
	global_store_dword v[24:25], v12, off offset:512
	global_store_dword v[24:25], v13, off offset:768
	global_store_dword v[26:27], v6, off
	global_store_dword v[26:27], v7, off offset:256
	global_store_dword v[26:27], v8, off offset:512
	global_store_dword v[26:27], v9, off offset:768
	v_add_co_u32_e32 v6, vcc, s18, v4
	s_mov_b32 s18, 0x1126f000
	s_nop 0
	v_addc_co_u32_e32 v7, vcc, 0, v5, vcc
	v_add_co_u32_e32 v4, vcc, s18, v4
	v_ashrrev_i32_e32 v1, 8, v35
	s_nop 0
	v_addc_co_u32_e32 v5, vcc, 0, v5, vcc
	v_add_u32_e32 v1, s28, v1
	global_store_dword v[4:5], v20, off offset:-4096
	global_store_dword v[6:7], v21, off offset:256
	global_store_dword v[6:7], v22, off offset:512
	global_store_dword v[6:7], v23, off offset:768
	global_store_dword v[4:5], v14, off
	global_store_dword v[4:5], v15, off offset:256
	global_store_dword v[4:5], v16, off offset:512
	global_store_dword v[4:5], v17, off offset:768
	v_ashrrev_i32_e32 v4, 3, v1
	v_ashrrev_i32_e32 v5, 31, v4
	v_lshrrev_b32_e32 v6, 4, v35
	v_lshlrev_b64 v[8:9], 4, v[4:5]
	v_and_or_b32 v8, v6, 15, v8
	v_lshlrev_b32_e32 v1, 6, v1
	v_lshlrev_b64 v[4:5], 11, v[8:9]
	v_and_b32_e32 v1, 0x1c0, v1
	v_lshl_add_u64 v[4:5], s[16:17], 0, v[4:5]
	v_lshlrev_b32_e32 v6, 2, v1
	v_mov_b32_e32 v7, v165
	v_lshl_add_u64 v[4:5], v[4:5], 0, v[6:7]
	v_lshlrev_b32_e32 v6, 2, v35
	v_and_b32_e32 v12, 60, v6
	v_lshlrev_b32_e32 v10, 2, v12
	v_mov_b32_e32 v11, v165
	v_lshl_add_u64 v[4:5], v[4:5], 0, v[10:11]
	s_waitcnt vmcnt(0)
	s_barrier
; #define LAS __attribute__((address_space(3)))
; __device__ __forceinline__ void scan_prompt_wg(const Params& P, LAS unsigned char* lds, int s, int h, int wave, int lane) {
;     ...
;         const int sl = wave, l15 = lane & 15, q4 = lane >> 4, e = 16 * sl + l15;
;         f32x4 S[4];
; #pragma unroll
;         for (int tau = 0; tau < 4; ++tau) S[tau] = (f32x4){0.f, 0.f, 0.f, 0.f};
;         const float* GT = (const float*)(P.ws + WS_GT) + (size_t)(s * 128) * 8 + h;
;         const v2u* Ug = (const v2u*)(ops0 + OPS_U) + (sl * 4) * 64 + lane;
;         v2u ua[4], ub[4];
; #pragma unroll
;         for (int tau = 0; tau < 4; ++tau) { ua[tau] = Ug[tau * 64]; ub[tau] = (Ug + step_stride / 8)[tau * 64]; }
;         SCAN_BAR();
;         int slot = 0;
;         float gt = GT[0];
; #pragma unroll 1
;         for (int n = 0; n < NST; ++n) {
;             const LAS unsigned char* ops = lds + slot * SR_SLOT;
;             const float gtn = (n + 1 < NST) ? GT[(size_t)(n + 1) * 8] : 0.f;
;             v2u uc[4];
; #pragma unroll
; __global__ void __launch_bounds__(NWAVES * 64, 2) fwd_kernel(Params P) {
;     ...
;                 const int pr = (int)blockIdx.x * 2 + (tid >> 8), sp = pr >> 3, hp_ = pr & 7, t = (tid >> 4) & 15, part = tid & 15;
;                 const size_t row = (size_t)sp * 16 + t;
;                 const f32x4 o4 = *(const f32x4*)((const float*)(ws + WS_OAS) + row * 512 + hp_ * 64 + 4 * part);
;                 float ss = (o4[0] * o4[0] + o4[1] * o4[1]) + (o4[2] * o4[2] + o4[3] * o4[3]);
;                 ss += __shfl_xor(ss, 1); ss += __shfl_xor(ss, 2); ss += __shfl_xor(ss, 4); ss += __shfl_xor(ss, 8);
;                 const float rstd = __builtin_amdgcn_rsqf(ss * (1.0f / 64.0f) + 1e-6f);
;                 const size_t mo = ((size_t)MP + row) * 1024 + hp_ * 64 + 4 * part;
;                 const v2u zb = *(const v2u*)((const bf16*)(ws + WS_Z) + mo);
;                 const f32x4 g4 = *(const f32x4*)(P.gdn_g + 4 * part);
;                 v2u o; o.x = pk2(o4[0] * rstd * g4[0] * siluf(bflo(zb.x)), o4[1] * rstd * g4[1] * siluf(bfhi(zb.x))); o.y = pk2(o4[2] * rstd * g4[2] * siluf(bflo(zb.y)), o4[3] * rstd * g4[3] * siluf(bfhi(zb.y)));
;                 *(v2u*)((bf16*)(ws + WS_MIX) + mo) = o;
;             }
;             __syncthreads();
;             REP(30) { scan_prompt_wg(P, lds, (int)blockIdx.x >> 3, (int)blockIdx.x & 7, wave, lane); __syncthreads(); }
	global_load_dwordx4 v[4:7], v[4:5], off
	v_lshlrev_b64 v[8:9], 10, v[8:9]
	v_or3_b32 v8, v8, v1, v12
	v_mov_b64_e32 v[12:13], 0x8000000
	v_lshl_add_u64 v[12:13], v[8:9], 1, v[12:13]
	v_lshl_add_u64 v[8:9], s[10:11], 0, v[12:13]
	global_load_dwordx2 v[14:15], v[8:9], off
	v_readlane_b32 s83, v247, 18
	v_mbcnt_lo_u32_b32 v1, -1, 0
	v_mbcnt_hi_u32_b32 v1, -1, v1
	v_xor_b32_e32 v53, 1, v1
	v_xor_b32_e32 v54, 2, v1
	v_xor_b32_e32 v55, 4, v1
	global_load_dwordx4 v[8:11], v10, s[82:83]
	v_xor_b32_e32 v56, 8, v1
	v_mov_b32_e32 v19, 0x358637bd
	s_mov_b64 s[46:47], s[82:83]
	s_mov_b64 s[16:17], -1
	s_cmp_lt_i32 s33, 4
	s_mul_hi_i32 s26, s0, 0x50000
	s_mul_i32 s27, s0, 0x50000
	s_mul_i32 s28, s2, 0xa000
	v_readlane_b32 s73, v247, 8
	v_readlane_b32 s74, v247, 9
	v_readlane_b32 s75, v247, 10
	v_readlane_b32 s76, v247, 11
	v_readlane_b32 s77, v247, 12
	v_readlane_b32 s78, v247, 13
	v_readlane_b32 s79, v247, 14
	v_readlane_b32 s80, v247, 15
	v_readlane_b32 s81, v247, 16
	v_readlane_b32 s84, v247, 19
	v_readlane_b32 s85, v247, 20
	v_readlane_b32 s86, v247, 21
	v_readlane_b32 s87, v247, 22
	s_waitcnt vmcnt(2)
	v_pk_mul_f32 v[16:17], v[6:7], v[6:7]
	v_pk_mul_f32 v[20:21], v[4:5], v[4:5]
	s_nop 0
	v_pk_mov_b32 v[22:23], v[20:21], v[16:17] op_sel:[1,0]
	v_mov_b32_e32 v21, v17
	v_pk_add_f32 v[16:17], v[22:23], v[20:21]
	s_nop 0
	v_add_f32_e32 v16, v16, v17
	v_and_b32_e32 v17, 64, v1
	v_add_u32_e32 v52, 64, v17
	v_cmp_lt_i32_e32 vcc, v53, v52
	s_nop 1
	v_cndmask_b32_e32 v17, v1, v53, vcc
	v_lshlrev_b32_e32 v57, 2, v17
	ds_bpermute_b32 v17, v57, v16
	v_cmp_lt_i32_e32 vcc, v54, v52
	s_waitcnt lgkmcnt(0)
	v_add_f32_e32 v16, v16, v17
	v_cndmask_b32_e32 v17, v1, v54, vcc
	v_lshlrev_b32_e32 v58, 2, v17
	ds_bpermute_b32 v17, v58, v16
	v_cmp_lt_i32_e32 vcc, v55, v52
	s_waitcnt lgkmcnt(0)
	v_add_f32_e32 v16, v16, v17
	v_cndmask_b32_e32 v17, v1, v55, vcc
	v_lshlrev_b32_e32 v17, 2, v17
	ds_bpermute_b32 v17, v17, v16
	v_cmp_lt_i32_e32 vcc, v56, v52
	s_waitcnt lgkmcnt(0)
	v_add_f32_e32 v16, v16, v17
	v_cndmask_b32_e32 v17, v1, v56, vcc
	v_lshlrev_b32_e32 v17, 2, v17
	ds_bpermute_b32 v17, v17, v16
	s_waitcnt lgkmcnt(0)
	v_add_f32_e32 v16, v16, v17
	v_fmac_f32_e32 v19, 0x3c800000, v16
	s_waitcnt vmcnt(1)
	v_lshlrev_b32_e32 v16, 16, v14
	v_and_b32_e32 v17, 0xffff0000, v14
	v_mul_f32_e32 v14, 0xbfb8aa3b, v16
	v_exp_f32_e32 v20, v14
	v_mul_f32_e32 v14, 0xbfb8aa3b, v17
	v_exp_f32_e32 v21, v14
	v_rsq_f32_e32 v14, v19
	v_add_f32_e32 v19, 1.0, v20
	v_rcp_f32_e32 v20, v19
	v_add_f32_e32 v19, 1.0, v21
	v_rcp_f32_e32 v21, v19
	v_pk_mul_f32 v[4:5], v[4:5], v[14:15] op_sel_hi:[1,0]
	s_waitcnt vmcnt(0)
	v_pk_mul_f32 v[4:5], v[8:9], v[4:5]
	v_pk_mul_f32 v[8:9], v[20:21], v[16:17]
	v_lshlrev_b32_e32 v16, 16, v15
	v_and_b32_e32 v17, 0xffff0000, v15
	v_mul_f32_e32 v15, 0xbfb8aa3b, v16
	v_mul_f32_e32 v19, 0xbfb8aa3b, v17
	v_exp_f32_e32 v15, v15
	v_exp_f32_e32 v19, v19
	v_pk_mul_f32 v[4:5], v[4:5], v[8:9]
	v_add_f32_e32 v8, 1.0, v15
	v_add_f32_e32 v9, 1.0, v19
	v_rcp_f32_e32 v8, v8
	v_rcp_f32_e32 v9, v9
	v_pk_mul_f32 v[6:7], v[6:7], v[14:15] op_sel_hi:[1,0]
	v_cvt_pk_bf16_f32 v4, v4, v5
	v_pk_mul_f32 v[6:7], v[10:11], v[6:7]
	v_pk_mul_f32 v[8:9], v[8:9], v[16:17]
	s_nop 0
	v_pk_mul_f32 v[6:7], v[6:7], v[8:9]
	s_nop 0
	v_cvt_pk_bf16_f32 v5, v6, v7
	v_lshl_add_u64 v[6:7], s[4:5], 0, v[12:13]
	global_store_dwordx2 v[6:7], v[4:5], off
	s_barrier
	s_cbranch_scc0 .LBB0_654
	s_lshl_b32 s16, s33, 8
	s_ashr_i32 s17, s16, 31
	s_lshl_b64 s[16:17], s[16:17], 3
	s_add_u32 s18, s12, s16
	s_addc_u32 s19, s13, s17
	v_lshl_add_u64 v[4:5], s[18:19], 0, v[2:3]
	v_add_co_u32_e32 v8, vcc, s31, v4
	s_mov_b32 s19, 0x58000
	s_nop 0
	v_addc_co_u32_e32 v9, vcc, 0, v5, vcc
	v_lshl_add_u64 v[6:7], v[4:5], 0, s[24:25]
	v_add_co_u32_e32 v4, vcc, s19, v4
	s_lshl_b64 s[14:15], s[14:15], 2
	s_nop 0
	v_addc_co_u32_e32 v5, vcc, 0, v5, vcc
	global_load_dwordx2 v[50:51], v[8:9], off nt
	global_load_dwordx2 v[48:49], v[6:7], off offset:512 nt
	global_load_dwordx2 v[46:47], v[6:7], off offset:1024 nt
	global_load_dwordx2 v[44:45], v[6:7], off offset:1536 nt
	global_load_dwordx2 v[22:23], v[4:5], off nt
	global_load_dwordx2 v[24:25], v[4:5], off offset:512 nt
	global_load_dwordx2 v[26:27], v[4:5], off offset:1024 nt
	global_load_dwordx2 v[28:29], v[4:5], off offset:1536 nt
	s_add_u32 s14, s29, s14
	s_addc_u32 s15, s30, s15
	s_lshl_b32 s18, s2, 2
	s_barrier
	v_mov_b32_e32 v4, s18
	global_load_dword v34, v4, s[14:15]
	s_lshl_b64 s[0:1], s[0:1], 5
	s_or_b32 s0, s0, s18
	v_readlane_b32 s18, v247, 0
	v_readlane_b32 s19, v247, 1
	s_add_u32 s0, s18, s0
	s_addc_u32 s1, s19, s1
	s_add_u32 s14, s0, 0x1400020
	s_addc_u32 s15, s1, 0
	s_add_u32 s0, s27, s28
	s_addc_u32 s1, s26, 0
	s_add_u32 s0, s0, s16
	s_addc_u32 s1, s1, s17
	v_lshrrev_b32_e32 v4, 2, v164
	s_add_u32 s0, s18, s0
	v_and_b32_e32 v73, 12, v4
	s_addc_u32 s1, s19, s1
	v_lshl_or_b32 v20, s33, 4, v30
	v_or_b32_e32 v72, 1, v73
	v_or_b32_e32 v71, 2, v73
	v_or_b32_e32 v70, 3, v4
	v_or_b32_e32 v69, 16, v73
	v_or_b32_e32 v68, 17, v73
	v_or_b32_e32 v67, 18, v73
	v_or_b32_e32 v66, 19, v4
	v_or_b32_e32 v65, 32, v73
	v_or_b32_e32 v64, 33, v73
	v_or_b32_e32 v63, 34, v73
	v_or_b32_e32 v62, 35, v4
	v_or_b32_e32 v61, 48, v73
	v_or_b32_e32 v60, 49, v73
	v_or_b32_e32 v59, 50, v73
	v_or_b32_e32 v19, 51, v4
	v_lshl_add_u64 v[2:3], s[0:1], 0, v[2:3]
	s_mov_b64 s[0:1], 0x239a8400
	s_mov_b32 s31, 0
	v_lshl_add_u32 v21, v20, 1, 0
	v_lshlrev_b32_e32 v74, 7, v73
	v_lshlrev_b32_e32 v75, 7, v72
	v_lshlrev_b32_e32 v76, 7, v71
	v_lshlrev_b32_e32 v77, 7, v70
	v_lshlrev_b32_e32 v78, 7, v69
	v_lshlrev_b32_e32 v79, 7, v68
	v_lshlrev_b32_e32 v80, 7, v67
	v_lshlrev_b32_e32 v81, 7, v66
	v_lshlrev_b32_e32 v82, 7, v65
	v_lshlrev_b32_e32 v83, 7, v64
	v_lshlrev_b32_e32 v84, 7, v63
	v_lshlrev_b32_e32 v85, 7, v62
	v_lshlrev_b32_e32 v86, 7, v61
	v_lshlrev_b32_e32 v87, 7, v60
	v_lshlrev_b32_e32 v88, 7, v59
	v_lshlrev_b32_e32 v89, 7, v19
	v_lshl_add_u32 v90, v164, 4, 0
	v_lshl_add_u64 v[30:31], v[2:3], 0, s[0:1]
	s_mov_b32 s29, 0x1e000
	s_mov_b64 s[16:17], 0x50000
	v_mov_b32_e32 v32, 0
	s_mov_b32 s30, 0
	v_mov_b32_e32 v14, v165
	v_mov_b32_e32 v15, v165
	v_mov_b32_e32 v16, v165
	v_mov_b32_e32 v17, v165
	v_mov_b32_e32 v10, v165
	v_mov_b32_e32 v11, v165
	v_mov_b32_e32 v12, v165
	v_mov_b32_e32 v13, v165
	v_mov_b32_e32 v2, v165
	v_mov_b32_e32 v3, v165
	v_mov_b32_e32 v4, v165
	v_mov_b32_e32 v5, v165
	v_mov_b32_e32 v6, v165
	v_mov_b32_e32 v7, v165
	v_mov_b32_e32 v8, v165
	v_mov_b32_e32 v9, v165
	s_branch .LBB0_643
.LBB0_641:
	global_load_dwordx2 v[28:29], v[30:31], off offset:512 nt

; __device__ __forceinline__ void scan_prompt_wg(const Params& P, LAS unsigned char* lds, int s, int h, int wave, int lane) {
;     ...
;             for (int tau = 0; tau < 4; ++tau) uc[tau] = (n + 2 < NST) ? (Ug + (size_t)(n + 2) * (step_stride / 8))[tau * 64] : (v2u){0u, 0u};
.LBB0_645:
	s_cmpk_lt_u32 s31, 0x7e
	s_cselect_b64 s[24:25], -1, 0
	s_cmpk_gt_u32 s31, 0x7d
	s_cbranch_scc1 .LBB0_649
	global_load_dwordx2 v[22:23], v[30:31], off offset:-1024 nt
	v_cndmask_b32_e64 v24, 0, 1, s[24:25]
	v_cmp_ne_u32_e64 s[0:1], 1, v24
	s_andn2_b64 vcc, exec, s[24:25]
	s_cbranch_vccz .LBB0_650

; __device__ __forceinline__ void scan_prompt_wg(const Params& P, LAS unsigned char* lds, int s, int h, int wave, int lane) {
;     ...
;             for (int tau = 0; tau < 4; ++tau) uc[tau] = (n + 2 < NST) ? (Ug + (size_t)(n + 2) * (step_stride / 8))[tau * 64] : (v2u){0u, 0u};
.LBB0_650:
	global_load_dwordx2 v[24:25], v[30:31], off offset:-512 nt
	s_and_b64 vcc, exec, s[0:1]
	s_cbranch_vccnz .LBB0_648
.LBB0_651:
	global_load_dwordx2 v[26:27], v[30:31], off nt
	s_and_b64 vcc, exec, s[0:1]
	s_cbranch_vccz .LBB0_641

; #define LAS __attribute__((address_space(3)))
; __device__ __forceinline__ void attn_group(const Params& P, LAS unsigned char* lds, const LAS float* tabh, int s, int h, int c0, int wave, int lane) {
;     const int pi = wave >> 1, qb = wave & 1, c = c0 + pi, l31 = lane & 31, hh = lane >> 5;
;     const unsigned char* yscr = (const unsigned char*)P.out;
;     const long kblk0 = (long)s * 256 + 2 * (c0 - 8);
;     const unsigned char* src = yscr + (wave < 4 ? YO_KF : YO_VF) + (size_t)h * 4096 + (size_t)(wave & 3) * 1024 + lane * 16;
;     LAS unsigned char* dstw = lds + (wave < 4 ? 0 : 4096) + (wave & 3) * 1024;
;     const int pos_lo = (c0 < 8) ? 2 * (8 - c0) : 0;
;     const bool fast = (c0 >= 8);
;     ...
;     bf16x8 qf[4];
;     { const unsigned char* qp = P.ws + WS_QF + ((size_t)(s * 256 + 2 * c + qb) * 8 + h) * 4096 + lane * 16;
; #pragma unroll
;       for (int kk = 0; kk < 4; ++kk) qf[kk] = *(const bf16x8*)(qp + kk * 1024);
; #pragma unroll
;       for (int kk = 0; kk < 4; ++kk) asm volatile("" : "+v"(qf[kk])); }
;     f32x16 cbias;
;     { const float bconst = tabh[256];
; #pragma unroll
;       for (int r = 0; r < 16; ++r) cbias[r] = bconst; }
; __global__ void __launch_bounds__(NWAVES * 64, 2) fwd_kernel(Params P) {
;     ...
;                 if (b >= 16u) { const unsigned g = b - 16u; const int sq = (int)(g >> 8), h = (int)((g >> 5) & 7), c0 = 4 * (int)(g & 31);
;                     attn_group(P, lds, (const LAS float*)(lds + TAB_OFF) + h * TAB_LD, sq, h, c0, wave, lane); }
.LBB0_722:
	s_and_b64 vcc, exec, s[38:39]
	s_cbranch_vccz .LBB0_728
	s_add_i32 s50, s50, -16
	s_lshl_b32 s38, s50, 2
	s_and_b32 s82, s38, 0x7c
	s_add_i32 s43, s82, s66
	s_lshl_b32 s39, s82, 1
	s_sub_i32 s84, 16, s39
	s_and_b32 s39, s50, 0xffffff00
	s_lshl_b32 s41, s43, 1
	s_add_i32 s41, s41, s39
	s_bfe_u32 s42, s50, 0x30005
	s_or_b32 s44, s41, s67
	s_mul_i32 s38, s42, 0xb00
	s_ashr_i32 s45, s44, 31
	s_lshr_b32 s10, s50, 8
	s_add_i32 s83, s38, 0
	s_lshl_b32 s40, s42, 12
	s_lshl_b64 s[44:45], s[44:45], 15
	s_add_u32 s39, s74, s44
	s_addc_u32 s41, s75, s45
	s_add_u32 s44, s39, s40
	s_addc_u32 s45, s41, 0
	v_lshl_add_u64 v[4:5], s[44:45], 0, v[166:167]
	global_load_dwordx4 v[68:71], v[4:5], off nt
	global_load_dwordx4 v[72:75], v[4:5], off offset:1024 nt
	global_load_dwordx4 v[76:79], v[4:5], off offset:2048 nt
	global_load_dwordx4 v[80:83], v[4:5], off offset:3072 nt
	s_mov_b32 s41, s11
	v_lshl_add_u64 v[4:5], v[180:181], 0, s[40:41]
	s_add_i32 s40, s83, 0x20600
	s_cmp_lt_u32 s82, 8
	v_mov_b32_e32 v2, s40
	s_cselect_b32 s44, s84, 0
	s_and_b32 s45, s50, 31
	s_lshl_b64 s[40:41], s[10:11], 23
	s_lshl_b32 s45, s45, 18
	s_or_b32 s40, s40, s45
	v_lshl_add_u64 v[4:5], v[4:5], 0, s[40:41]
	s_mov_b32 s40, 0xfff80000
	s_mov_b32 s41, -1
	s_mov_b32 s39, 0
	v_lshl_add_u64 v[6:7], v[4:5], 0, s[40:41]
	s_mov_b32 s40, s72
	s_waitcnt vmcnt(3)
	s_waitcnt vmcnt(2)
	s_waitcnt vmcnt(1)
	s_waitcnt vmcnt(0)
	ds_read_b32 v36, v2
	s_branch .LBB0_725

; #define LAS __attribute__((address_space(3)))
; __device__ __forceinline__ float siluf(float x) { return x * __builtin_amdgcn_rcpf(1.0f + __expf(-x)); }
; __device__ __forceinline__ void unpack8(v4u w, float (&f)[8]) { f[0] = bflo(w.x); f[1] = bfhi(w.x); f[2] = bflo(w.y); f[3] = bfhi(w.y); f[4] = bflo(w.z); f[5] = bfhi(w.z); f[6] = bflo(w.w); f[7] = bfhi(w.w); }
; __device__ __forceinline__ v4u packf8(const float (&f)[8]) { v4u w; w.x = pk2(f[0], f[1]); w.y = pk2(f[2], f[3]); w.z = pk2(f[4], f[5]); w.w = pk2(f[6], f[7]); return w; }
; __device__ __forceinline__ void attn_group(const Params& P, LAS unsigned char* lds, const LAS float* tabh, int s, int h, int c0, int wave, int lane) {
;     ...
;     {
;         const float l = lsum + __shfl_xor(lsum, 32); const float inv = __builtin_amdgcn_rcpf(l);
;         const size_t mrow0 = (size_t)s * TP + c * 64 + 32 * qb;
;         const bf16* Z = (const bf16*)(P.ws + WS_Z) + mrow0 * 1024 + 512 + h * 64; bf16* MIX = (bf16*)(P.ws + WS_MIX) + mrow0 * 1024 + 512 + h * 64;
;         const int rr = lane >> 3, pc = lane & 7;
;         v4u zb[4];
; #pragma unroll
;         for (int ps = 0; ps < 4; ++ps) zb[ps] = *(const v4u*)(Z + (size_t)(8 * ps + rr) * 1024 + 8 * pc);
;         LAS unsigned char* st = lds + wave * 14336;
; #pragma unroll
;         for (int dt = 0; dt < 2; ++dt)
; #pragma unroll
;             for (int rg = 0; rg < 4; ++rg) { const f32x4 o = {oacc[dt][4 * rg] * inv, oacc[dt][4 * rg + 1] * inv, oacc[dt][4 * rg + 2] * inv, oacc[dt][4 * rg + 3] * inv};
;                 *(LAS f32x4*)(st + l31 * 272 + (32 * dt + 8 * rg + 4 * hh) * 4) = o; }
; #pragma unroll
;         for (int ps = 0; ps < 4; ++ps) { const int row = 8 * ps + rr;
;             const f32x4 a = *(const LAS f32x4*)(st + row * 272 + pc * 32), b = *(const LAS f32x4*)(st + row * 272 + pc * 32 + 16);
;             float z[8]; unpack8(zb[ps], z);
;             float f[8] = {a[0] * siluf(z[0]), a[1] * siluf(z[1]), a[2] * siluf(z[2]), a[3] * siluf(z[3]), b[0] * siluf(z[4]), b[1] * siluf(z[5]), b[2] * siluf(z[6]), b[3] * siluf(z[7])};
;             *(v4u*)(MIX + (size_t)row * 1024 + 8 * pc) = packf8(f); }
.LBB0_743:
	s_lshl_b64 s[38:39], s[10:11], 13
	s_lshl_b32 s10, s43, 6
	s_ashr_i32 s40, s10, 31
	s_add_u32 s38, s38, s10
	s_addc_u32 s39, s39, s40
	s_or_b64 s[38:39], s[38:39], s[16:17]
	s_lshl_b64 s[38:39], s[38:39], 11
	v_readlane_b32 s40, v247, 0
	v_readlane_b32 s41, v247, 1
	s_add_u32 s10, s40, s38
	s_addc_u32 s39, s41, s39
	s_lshl_b32 s38, s42, 7
	s_add_u32 s38, s10, s38
	v_lshlrev_b32_e32 v2, 1, v174
	s_addc_u32 s39, s39, 0
	v_lshlrev_b32_e32 v36, 1, v176
	v_mov_b32_e32 v37, v3
	v_lshl_add_u64 v[46:47], s[38:39], 0, v[2:3]
	v_lshl_add_u64 v[48:49], v[46:47], 0, v[36:37]
	v_add_co_u32_e32 v38, vcc, s78, v48
	ds_bpermute_b32 v2, v1, v118
	s_nop 0
	v_addc_co_u32_e32 v39, vcc, 0, v49, vcc
	global_load_dwordx4 v[38:41], v[38:39], off offset:1024 nt
	v_add_co_u32_e32 v42, vcc, s79, v48
	s_waitcnt lgkmcnt(0)
	v_add_f32_e32 v2, v118, v2
	v_addc_co_u32_e32 v43, vcc, 0, v49, vcc
	global_load_dwordx4 v[42:45], v[42:43], off offset:1024 nt
	v_rcp_f32_e32 v2, v2
	v_mov_b32_e32 v183, v3
	v_mov_b32_e32 v185, v3
	v_pk_mul_f32 v[20:21], v[20:21], v[2:3] op_sel_hi:[1,0]
	v_pk_mul_f32 v[22:23], v[22:23], v[2:3] op_sel_hi:[1,0]
	v_pk_mul_f32 v[4:5], v[4:5], v[2:3] op_sel_hi:[1,0]
	v_pk_mul_f32 v[24:25], v[24:25], v[2:3] op_sel_hi:[1,0]
	v_pk_mul_f32 v[26:27], v[26:27], v[2:3] op_sel_hi:[1,0]
	v_pk_mul_f32 v[28:29], v[28:29], v[2:3] op_sel_hi:[1,0]
	v_pk_mul_f32 v[30:31], v[30:31], v[2:3] op_sel_hi:[1,0]
	v_pk_mul_f32 v[32:33], v[32:33], v[2:3] op_sel_hi:[1,0]
	v_pk_mul_f32 v[34:35], v[34:35], v[2:3] op_sel_hi:[1,0]
	v_pk_mul_f32 v[6:7], v[6:7], v[2:3] op_sel_hi:[1,0]
	v_pk_mul_f32 v[8:9], v[8:9], v[2:3] op_sel_hi:[1,0]
	v_pk_mul_f32 v[10:11], v[10:11], v[2:3] op_sel_hi:[1,0]
	v_pk_mul_f32 v[12:13], v[12:13], v[2:3] op_sel_hi:[1,0]
	v_pk_mul_f32 v[14:15], v[14:15], v[2:3] op_sel_hi:[1,0]
	v_pk_mul_f32 v[16:17], v[16:17], v[2:3] op_sel_hi:[1,0]
	v_pk_mul_f32 v[18:19], v[18:19], v[2:3] op_sel_hi:[1,0]
	ds_write_b128 v213, v[20:23]
	ds_write_b128 v213, v[24:27] offset:32
	ds_write_b128 v213, v[28:31] offset:64
	ds_write_b128 v213, v[32:35] offset:96
	ds_write_b128 v213, v[4:7] offset:128
	ds_write_b128 v213, v[8:11] offset:160
	ds_write_b128 v213, v[12:15] offset:192
	ds_write_b128 v213, v[16:19] offset:224
	v_add_co_u32_e32 v4, vcc, s80, v48
	ds_read_b128 v[14:17], v214
	ds_read_b128 v[18:21], v214 offset:16
	v_addc_co_u32_e32 v5, vcc, 0, v49, vcc
	v_add_co_u32_e32 v6, vcc, s81, v48
	v_lshl_add_u64 v[12:13], v[46:47], 0, s[34:35]
	s_nop 0
	v_addc_co_u32_e32 v7, vcc, 0, v49, vcc
	global_load_dwordx4 v[8:11], v[4:5], off offset:1024 nt
	s_nop 0
	global_load_dwordx4 v[4:7], v[6:7], off offset:1024 nt
	s_waitcnt vmcnt(3)
	v_lshlrev_b32_e32 v22, 16, v38
	v_and_b32_e32 v23, 0xffff0000, v38
	v_lshlrev_b32_e32 v24, 16, v39
	v_mul_f32_e32 v2, 0xbfb8aa3b, v22
	v_mul_f32_e32 v30, 0xbfb8aa3b, v23
	v_mul_f32_e32 v31, 0xbfb8aa3b, v24
	v_exp_f32_e32 v2, v2
	v_exp_f32_e32 v30, v30
	v_exp_f32_e32 v31, v31
	v_lshlrev_b32_e32 v28, 16, v41
	v_mul_f32_e32 v35, 0xbfb8aa3b, v28
	v_and_b32_e32 v25, 0xffff0000, v39
	v_and_b32_e32 v29, 0xffff0000, v41
	v_exp_f32_e32 v39, v35
	v_add_f32_e32 v2, 1.0, v2
	v_add_f32_e32 v35, 1.0, v30
	v_lshlrev_b32_e32 v26, 16, v40
	v_and_b32_e32 v27, 0xffff0000, v40
	v_mul_f32_e32 v32, 0xbfb8aa3b, v25
	v_mul_f32_e32 v38, 0xbfb8aa3b, v29
	v_add_f32_e32 v40, 1.0, v31
	v_rcp_f32_e32 v30, v2
	v_rcp_f32_e32 v31, v35
	v_mul_f32_e32 v33, 0xbfb8aa3b, v26
	v_mul_f32_e32 v34, 0xbfb8aa3b, v27
	v_exp_f32_e32 v32, v32
	v_exp_f32_e32 v38, v38
	v_exp_f32_e32 v33, v33
	v_exp_f32_e32 v34, v34
	v_pk_mul_f32 v[22:23], v[30:31], v[22:23]
	v_add_f32_e32 v2, 1.0, v39
	v_add_f32_e32 v41, 1.0, v32
	s_waitcnt lgkmcnt(1)
	v_pk_mul_f32 v[14:15], v[22:23], v[14:15]
	v_rcp_f32_e32 v22, v2
	v_add_f32_e32 v2, 1.0, v38
	v_add_f32_e32 v46, 1.0, v33
	v_add_f32_e32 v47, 1.0, v34
	v_rcp_f32_e32 v32, v40
	v_rcp_f32_e32 v33, v41
	v_rcp_f32_e32 v23, v2
	v_rcp_f32_e32 v34, v46
	v_rcp_f32_e32 v35, v47
	v_pk_mul_f32 v[24:25], v[32:33], v[24:25]
	v_pk_mul_f32 v[22:23], v[22:23], v[28:29]
	v_pk_mul_f32 v[16:17], v[24:25], v[16:17]
	v_pk_mul_f32 v[24:25], v[34:35], v[26:27]
	s_waitcnt lgkmcnt(0)
	v_pk_mul_f32 v[20:21], v[22:23], v[20:21]
	s_waitcnt vmcnt(2)
	v_lshlrev_b32_e32 v22, 16, v42
	v_pk_mul_f32 v[18:19], v[24:25], v[18:19]
	v_and_b32_e32 v23, 0xffff0000, v42
	v_mul_f32_e32 v2, 0xbfb8aa3b, v22
	v_cvt_pk_bf16_f32 v14, v14, v15
	v_cvt_pk_bf16_f32 v15, v16, v17
	v_cvt_pk_bf16_f32 v16, v18, v19
	v_exp_f32_e32 v2, v2
	v_mul_f32_e32 v18, 0xbfb8aa3b, v23
	v_cvt_pk_bf16_f32 v17, v20, v21
	v_exp_f32_e32 v20, v18
	v_add_f32_e32 v2, 1.0, v2
	v_rcp_f32_e32 v24, v2
	v_lshl_add_u64 v[18:19], v[12:13], 0, v[36:37]
	v_add_f32_e32 v2, 1.0, v20
	v_rcp_f32_e32 v25, v2
	global_store_dwordx4 v[18:19], v[14:17], off
	ds_read_b128 v[14:17], v214 offset:2176
	ds_read_b128 v[18:21], v214 offset:2192
	v_and_b32_e32 v27, 0xffff0000, v44
	v_pk_mul_f32 v[22:23], v[24:25], v[22:23]
	v_lshlrev_b32_e32 v24, 16, v43
	v_and_b32_e32 v25, 0xffff0000, v43
	v_mul_f32_e32 v2, 0xbfb8aa3b, v24
	v_exp_f32_e32 v2, v2
	v_mul_f32_e32 v26, 0xbfb8aa3b, v25
	v_exp_f32_e32 v26, v26
	s_waitcnt lgkmcnt(1)
; #define LAS __attribute__((address_space(3)))
; __device__ __forceinline__ float siluf(float x) { return x * __builtin_amdgcn_rcpf(1.0f + __expf(-x)); }
; __device__ __forceinline__ void unpack8(v4u w, float (&f)[8]) { f[0] = bflo(w.x); f[1] = bfhi(w.x); f[2] = bflo(w.y); f[3] = bfhi(w.y); f[4] = bflo(w.z); f[5] = bfhi(w.z); f[6] = bflo(w.w); f[7] = bfhi(w.w); }
; __device__ __forceinline__ v4u packf8(const float (&f)[8]) { v4u w; w.x = pk2(f[0], f[1]); w.y = pk2(f[2], f[3]); w.z = pk2(f[4], f[5]); w.w = pk2(f[6], f[7]); return w; }
; __device__ __forceinline__ void attn_group(const Params& P, LAS unsigned char* lds, const LAS float* tabh, int s, int h, int c0, int wave, int lane) {
;     ...
;         for (int ps = 0; ps < 4; ++ps) { const int row = 8 * ps + rr;
;             const f32x4 a = *(const LAS f32x4*)(st + row * 272 + pc * 32), b = *(const LAS f32x4*)(st + row * 272 + pc * 32 + 16);
;             float z[8]; unpack8(zb[ps], z);
;             float f[8] = {a[0] * siluf(z[0]), a[1] * siluf(z[1]), a[2] * siluf(z[2]), a[3] * siluf(z[3]), b[0] * siluf(z[4]), b[1] * siluf(z[5]), b[2] * siluf(z[6]), b[3] * siluf(z[7])};
;             *(v4u*)(MIX + (size_t)row * 1024 + 8 * pc) = packf8(f); }
	v_pk_mul_f32 v[14:15], v[22:23], v[14:15]
	v_add_f32_e32 v2, 1.0, v2
	v_rcp_f32_e32 v22, v2
	v_add_f32_e32 v2, 1.0, v26
	v_lshlrev_b32_e32 v26, 16, v44
	v_rcp_f32_e32 v23, v2
	v_mul_f32_e32 v2, 0xbfb8aa3b, v26
	v_exp_f32_e32 v2, v2
	v_mul_f32_e32 v28, 0xbfb8aa3b, v27
	v_exp_f32_e32 v28, v28
	v_pk_mul_f32 v[22:23], v[22:23], v[24:25]
	v_add_f32_e32 v2, 1.0, v2
	v_rcp_f32_e32 v24, v2
	v_add_f32_e32 v2, 1.0, v28
	v_lshlrev_b32_e32 v28, 16, v45
	v_and_b32_e32 v29, 0xffff0000, v45
	v_mul_f32_e32 v25, 0xbfb8aa3b, v28
	v_exp_f32_e32 v30, v25
	v_mul_f32_e32 v25, 0xbfb8aa3b, v29
	v_exp_f32_e32 v31, v25
	v_rcp_f32_e32 v25, v2
	v_add_f32_e32 v2, 1.0, v30
	v_rcp_f32_e32 v30, v2
	v_add_f32_e32 v2, 1.0, v31
	v_rcp_f32_e32 v31, v2
	v_pk_mul_f32 v[16:17], v[22:23], v[16:17]
	v_pk_mul_f32 v[22:23], v[24:25], v[26:27]
	v_cvt_pk_bf16_f32 v14, v14, v15
	s_waitcnt lgkmcnt(0)
	v_pk_mul_f32 v[18:19], v[22:23], v[18:19]
	v_pk_mul_f32 v[22:23], v[30:31], v[28:29]
	v_cvt_pk_bf16_f32 v15, v16, v17
	v_pk_mul_f32 v[20:21], v[22:23], v[20:21]
	s_waitcnt vmcnt(2)
	v_lshlrev_b32_e32 v22, 16, v8
	v_and_b32_e32 v23, 0xffff0000, v8
	v_mul_f32_e32 v8, 0xbfb8aa3b, v22
	v_cvt_pk_bf16_f32 v16, v18, v19
	v_exp_f32_e32 v8, v8
	v_mul_f32_e32 v18, 0xbfb8aa3b, v23
	v_cvt_pk_bf16_f32 v17, v20, v21
	v_exp_f32_e32 v20, v18
	v_lshlrev_b32_e32 v2, 1, v178
	v_lshl_add_u64 v[18:19], v[12:13], 0, v[2:3]
	v_add_f32_e32 v2, 1.0, v8
	v_rcp_f32_e32 v24, v2
	v_add_f32_e32 v2, 1.0, v20
	v_rcp_f32_e32 v25, v2
	v_lshlrev_b32_e32 v8, 16, v9
	v_and_b32_e32 v9, 0xffff0000, v9
	v_mul_f32_e32 v2, 0xbfb8aa3b, v8
	global_store_dwordx4 v[18:19], v[14:17], off
	v_pk_mul_f32 v[22:23], v[24:25], v[22:23]
	v_exp_f32_e32 v2, v2
	v_mul_f32_e32 v24, 0xbfb8aa3b, v9
	ds_read_b128 v[14:17], v214 offset:4352
	ds_read_b128 v[18:21], v214 offset:4368
	v_exp_f32_e32 v24, v24
	v_add_f32_e32 v2, 1.0, v2
	v_and_b32_e32 v25, 0xffff0000, v10
	s_waitcnt lgkmcnt(1)
	v_pk_mul_f32 v[14:15], v[22:23], v[14:15]
	v_rcp_f32_e32 v22, v2
	v_add_f32_e32 v2, 1.0, v24
	v_lshlrev_b32_e32 v24, 16, v10
	v_rcp_f32_e32 v23, v2
	v_mul_f32_e32 v2, 0xbfb8aa3b, v24
	v_exp_f32_e32 v2, v2
	v_mul_f32_e32 v10, 0xbfb8aa3b, v25
	v_exp_f32_e32 v26, v10
	v_pk_mul_f32 v[8:9], v[22:23], v[8:9]
	v_lshlrev_b32_e32 v22, 16, v11
	v_add_f32_e32 v2, 1.0, v2
	v_and_b32_e32 v23, 0xffff0000, v11
	v_mul_f32_e32 v11, 0xbfb8aa3b, v22
	v_rcp_f32_e32 v10, v2
	v_add_f32_e32 v2, 1.0, v26
	v_exp_f32_e32 v26, v11
	v_mul_f32_e32 v11, 0xbfb8aa3b, v23
	v_exp_f32_e32 v27, v11
	v_rcp_f32_e32 v11, v2
	v_add_f32_e32 v2, 1.0, v26
	v_rcp_f32_e32 v26, v2
	v_add_f32_e32 v2, 1.0, v27
	v_rcp_f32_e32 v27, v2
	v_pk_mul_f32 v[16:17], v[8:9], v[16:17]
	v_pk_mul_f32 v[8:9], v[10:11], v[24:25]
	s_waitcnt lgkmcnt(0)
	v_pk_mul_f32 v[10:11], v[8:9], v[18:19]
	v_pk_mul_f32 v[8:9], v[26:27], v[22:23]
	v_cvt_pk_bf16_f32 v10, v10, v11
	v_pk_mul_f32 v[18:19], v[8:9], v[20:21]
	v_cvt_pk_bf16_f32 v8, v14, v15
	v_cvt_pk_bf16_f32 v11, v18, v19
	s_waitcnt vmcnt(2)
	v_lshlrev_b32_e32 v18, 16, v4
	v_and_b32_e32 v19, 0xffff0000, v4
	v_mul_f32_e32 v2, 0xbfb8aa3b, v18
	v_exp_f32_e32 v2, v2
	v_mul_f32_e32 v4, 0xbfb8aa3b, v19
	v_exp_f32_e32 v4, v4
	v_cvt_pk_bf16_f32 v9, v16, v17
	v_add_f32_e32 v2, 1.0, v2
	v_rcp_f32_e32 v20, v2
	v_add_f32_e32 v2, 1.0, v4
	v_rcp_f32_e32 v21, v2
	v_lshlrev_b32_e32 v4, 16, v5
	v_lshl_add_u64 v[14:15], v[12:13], 0, v[182:183]
	v_and_b32_e32 v5, 0xffff0000, v5
	v_mul_f32_e32 v2, 0xbfb8aa3b, v4
	global_store_dwordx4 v[14:15], v[8:11], off
	v_pk_mul_f32 v[18:19], v[20:21], v[18:19]
	v_exp_f32_e32 v2, v2
	v_mul_f32_e32 v20, 0xbfb8aa3b, v5
	ds_read_b128 v[8:11], v214 offset:6528
	ds_read_b128 v[14:17], v214 offset:6544
	v_exp_f32_e32 v20, v20
	v_add_f32_e32 v2, 1.0, v2
	v_and_b32_e32 v21, 0xffff0000, v6
	s_waitcnt lgkmcnt(1)
	v_pk_mul_f32 v[8:9], v[18:19], v[8:9]
	v_rcp_f32_e32 v18, v2
	v_add_f32_e32 v2, 1.0, v20
	v_lshlrev_b32_e32 v20, 16, v6
	v_rcp_f32_e32 v19, v2
	v_mul_f32_e32 v2, 0xbfb8aa3b, v20
	v_exp_f32_e32 v2, v2
	v_mul_f32_e32 v6, 0xbfb8aa3b, v21
	v_exp_f32_e32 v22, v6
	v_pk_mul_f32 v[4:5], v[18:19], v[4:5]
	v_lshlrev_b32_e32 v18, 16, v7
	v_add_f32_e32 v2, 1.0, v2
	v_and_b32_e32 v19, 0xffff0000, v7
	v_mul_f32_e32 v7, 0xbfb8aa3b, v18
	v_rcp_f32_e32 v6, v2
	v_add_f32_e32 v2, 1.0, v22
	v_exp_f32_e32 v22, v7
	v_mul_f32_e32 v7, 0xbfb8aa3b, v19
	v_exp_f32_e32 v23, v7
	v_rcp_f32_e32 v7, v2
	v_add_f32_e32 v2, 1.0, v22
	v_rcp_f32_e32 v22, v2
	v_add_f32_e32 v2, 1.0, v23
	v_rcp_f32_e32 v23, v2
	v_pk_mul_f32 v[10:11], v[4:5], v[10:11]
	v_pk_mul_f32 v[4:5], v[6:7], v[20:21]
	s_waitcnt lgkmcnt(0)
	v_pk_mul_f32 v[6:7], v[4:5], v[14:15]
	v_pk_mul_f32 v[4:5], v[22:23], v[18:19]
	v_cvt_pk_bf16_f32 v6, v6, v7
	v_pk_mul_f32 v[14:15], v[4:5], v[16:17]
	v_cvt_pk_bf16_f32 v4, v8, v9
	v_cvt_pk_bf16_f32 v5, v10, v11
	v_cvt_pk_bf16_f32 v7, v14, v15
	v_lshl_add_u64 v[8:9], v[12:13], 0, v[184:185]
	global_store_dwordx4 v[8:9], v[4:7], off
	s_and_saveexec_b64 s[38:39], s[0:1]
	s_cbranch_execz .LBB0_697
